# P6 expert-weight conversion: the eight serialised dwordx4 loads per tile pair issued together into spare registers with counted vmcnt waits (hazard slots kept)
# baseline (speedup 1.0000x reference)
; #define PIN(i) (*(const float* const __attribute__((address_space(4)))*)(KA + 8 * (i)))
; DEVI void expert_tt_pair(const int TIDX, KAP KA, unsigned char* WSB, int l, int p, unsigned char* smem) {
;   float* tile = (float*)smem;
;   bf16_t* WE = (bf16_t*)(WSB + O_WE);
;   const int t = TIDX, n4 = (t & 15) * 4, kr = t >> 4, kc = (t & 7) * 8, nr = t >> 3;
;   const int mat = p >> 6, tp = (p & 63) * 2, kind = mat >> 5, e = mat & 31;
;   const float* src = PIN(kind == 0 ? I_WE1 : (kind == 1 ? I_WE3 : I_WE2)) + ((size_t)l * 32 + e) * 524288;
;   bf16_t* dst = WE + ((size_t)kind * 32 + e) * 524288;
;   const int ld = kind < 2 ? 512 : 1024, K = kind < 2 ? 1024 : 512, nkt = K >> 6;
;   int k0[2], n0[2];
; #pragma unroll
;   for (int u = 0; u < 2; ++u) { const int tt = tp + u; k0[u] = (tt % nkt) * 64; n0[u] = (tt / nkt) * 64; }
;   float4 v[2][4];
; #pragma unroll
;   for (int u = 0; u < 2; ++u)
; #pragma unroll
;     for (int q = 0; q < 4; ++q) v[u][q] = *(const float4*)(src + (size_t)(k0[u] + kr + 16 * q) * ld + n0[u] + n4);
; #pragma unroll
;   for (int u = 0; u < 2; ++u)
; #pragma unroll
;     for (int q = 0; q < 4; ++q) {
;       float* d = tile + u * 4160 + (kr + 16 * q) * 65 + n4;
;       d[0] = v[u][q].x; d[1] = v[u][q].y; d[2] = v[u][q].z; d[3] = v[u][q].w;
;     }
;   __syncthreads();
.LBB0_108:
	s_and_b32 s25, s6, 0x7e
	s_ashr_i32 s26, s8, 11
	s_bfe_u32 s7, s8, 0x50006
	s_cmp_eq_u32 s26, 1
	s_cselect_b32 s27, s43, 0xd0
	s_cmpk_gt_u32 s8, 0x7ff
	s_cselect_b32 s27, s27, 0xc0
	s_add_u32 s28, s88, s27
	s_addc_u32 s29, s89, 0
	s_ashr_i32 s27, s26, 31
	s_load_dwordx2 s[30:31], s[28:29], 0x0
	s_lshl_b32 s36, s7, 21
	s_lshl_b64 s[34:35], s[26:27], 25
	s_lshl_b32 s29, s7, 20
	s_cmp_lt_i32 s26, 2
	s_cselect_b32 s37, 4, 3
	s_cselect_b32 s26, 15, 7
	s_cselect_b32 s38, 9, 10
	s_cselect_b32 s7, 10, 9
	s_lshr_b32 s39, s25, s37
	s_or_b32 s25, s25, 1
	s_lshr_b32 s37, s25, s37
	s_and_b32 s28, s26, s6
	s_lshl_b32 s27, s39, 6
	s_and_b32 s26, s25, s26
	s_lshl_b32 s25, s37, 6
	s_waitcnt lgkmcnt(0)
	s_add_u32 s30, s30, s2
	s_addc_u32 s31, s31, s3
	s_add_u32 s30, s30, s36
	s_addc_u32 s31, s31, 0
	v_lshl_add_u64 v[0:1], s[30:31], 0, v[128:129]
	v_lshl_add_u32 v2, s28, 6, v78
	s_add_u32 s30, s16, s34
	s_addc_u32 s31, s17, s35
	s_lshl_b32 s54, s39, 8
	v_ashrrev_i32_e32 v3, 31, v2
	v_lshl_add_u64 v[4:5], v[0:1], 0, s[54:55]
	v_lshlrev_b64 v[6:7], s38, v[2:3]
	v_lshl_add_u64 v[16:17], v[6:7], 2, v[4:5]
	v_add_u32_e32 v6, 16, v2
	v_ashrrev_i32_e32 v7, 31, v6
	v_lshlrev_b64 v[6:7], s38, v[6:7]
	v_lshl_add_u64 v[18:19], v[6:7], 2, v[4:5]
	v_add_u32_e32 v6, 32, v2
	v_add_u32_e32 v2, 48, v2
	v_ashrrev_i32_e32 v3, 31, v2
	v_lshlrev_b64 v[2:3], s38, v[2:3]
	v_ashrrev_i32_e32 v7, 31, v6
	v_lshl_add_u64 v[12:13], v[2:3], 2, v[4:5]
	v_lshl_add_u32 v2, s26, 6, v78
	v_lshlrev_b64 v[6:7], s38, v[6:7]
	s_lshl_b32 s54, s37, 8
	v_ashrrev_i32_e32 v3, 31, v2
	v_lshl_add_u64 v[14:15], v[6:7], 2, v[4:5]
	v_lshl_add_u64 v[0:1], v[0:1], 0, s[54:55]
	v_lshlrev_b64 v[4:5], s38, v[2:3]
	v_lshl_add_u64 v[10:11], v[4:5], 2, v[0:1]
	v_add_u32_e32 v4, 16, v2
	v_ashrrev_i32_e32 v5, 31, v4
	v_lshlrev_b64 v[4:5], s38, v[4:5]
	v_lshl_add_u64 v[8:9], v[4:5], 2, v[0:1]
	v_add_u32_e32 v4, 32, v2
	v_add_u32_e32 v2, 48, v2
	v_ashrrev_i32_e32 v5, 31, v4
	v_ashrrev_i32_e32 v3, 31, v2
	v_lshlrev_b64 v[4:5], s38, v[4:5]
	v_lshlrev_b64 v[2:3], s38, v[2:3]
	v_lshl_add_u64 v[6:7], v[4:5], 2, v[0:1]
	v_lshl_add_u64 v[4:5], v[2:3], 2, v[0:1]
	global_load_dwordx4 v[132:135], v[16:17], off
	global_load_dwordx4 v[136:139], v[18:19], off
	global_load_dwordx4 v[140:143], v[14:15], off
	global_load_dwordx4 v[144:147], v[12:13], off
	global_load_dwordx4 v[148:151], v[10:11], off
	global_load_dwordx4 v[152:155], v[8:9], off
	global_load_dwordx4 v[156:159], v[6:7], off
	global_load_dwordx4 v[162:165], v[4:5], off
	v_add_u32_e32 v16, 0x1040, v82
	s_add_u32 s30, s30, s29
	s_addc_u32 s31, s31, 0
	v_mov_b32_e32 v65, v129
	v_add_u32_e32 v24, s27, v79
	s_lshl_b32 s54, s28, 7
	v_ashrrev_i32_e32 v25, 31, v24
	v_lshlrev_b64 v[24:25], s7, v[24:25]
	s_add_i32 s8, s8, s84
	s_waitcnt vmcnt(7)
	v_mov_b32_e32 v0, v132
	v_mov_b32_e32 v1, v133
	v_mov_b32_e32 v2, v134
	v_mov_b32_e32 v3, v135
	ds_write2_b32 v82, v0, v1 offset1:1
	ds_write2_b32 v82, v2, v3 offset0:2 offset1:3
	s_nop 0
	s_waitcnt vmcnt(6)
	v_mov_b32_e32 v0, v136
	v_mov_b32_e32 v1, v137
	v_mov_b32_e32 v2, v138
	v_mov_b32_e32 v3, v139
	ds_write2_b32 v16, v0, v1 offset1:1
	v_add_u32_e32 v0, 0x1048, v82
	ds_write2_b32 v0, v2, v3 offset1:1
	s_nop 0
	v_add_u32_e32 v14, 0x2080, v82
	s_waitcnt vmcnt(5)
	v_mov_b32_e32 v0, v140
	v_mov_b32_e32 v1, v141
	v_mov_b32_e32 v2, v142
	v_mov_b32_e32 v3, v143
	ds_write2_b32 v14, v0, v1 offset1:1
	v_add_u32_e32 v0, 0x2088, v82
	ds_write2_b32 v0, v2, v3 offset1:1
	s_nop 0
	v_add_u32_e32 v12, 0x30c0, v82
	s_waitcnt vmcnt(4)
	v_mov_b32_e32 v0, v144
	v_mov_b32_e32 v1, v145
	v_mov_b32_e32 v2, v146
	v_mov_b32_e32 v3, v147
	ds_write2_b32 v12, v0, v1 offset1:1
	v_add_u32_e32 v0, 0x30c8, v82
	ds_write2_b32 v0, v2, v3 offset1:1
	s_nop 0
	v_add_u32_e32 v10, 0x4100, v82
	s_waitcnt vmcnt(3)
	v_mov_b32_e32 v0, v148
	v_mov_b32_e32 v1, v149
	v_mov_b32_e32 v2, v150
	v_mov_b32_e32 v3, v151
	ds_write2_b32 v10, v0, v1 offset1:1
	v_add_u32_e32 v0, 0x4108, v82
	ds_write2_b32 v0, v2, v3 offset1:1
	s_nop 0
	v_add_u32_e32 v8, 0x5140, v82
	s_waitcnt vmcnt(2)
	v_mov_b32_e32 v0, v152
	v_mov_b32_e32 v1, v153
	v_mov_b32_e32 v2, v154
	v_mov_b32_e32 v3, v155
	ds_write2_b32 v8, v0, v1 offset1:1
	v_add_u32_e32 v0, 0x5148, v82
	ds_write2_b32 v0, v2, v3 offset1:1
	s_nop 0
	v_add_u32_e32 v6, 0x6180, v82
	s_waitcnt vmcnt(1)
	v_mov_b32_e32 v0, v156
	v_mov_b32_e32 v1, v157
	v_mov_b32_e32 v2, v158
	v_mov_b32_e32 v3, v159
	ds_write2_b32 v6, v0, v1 offset1:1
	v_add_u32_e32 v0, 0x6188, v82
	ds_write2_b32 v0, v2, v3 offset1:1
	s_nop 0
	v_add_u32_e32 v4, 0x71c0, v82
	s_waitcnt vmcnt(0)
	v_mov_b32_e32 v0, v162
	v_mov_b32_e32 v1, v163
	v_mov_b32_e32 v2, v164
	v_mov_b32_e32 v3, v165
	ds_write2_b32 v4, v0, v1 offset1:1
	v_add_u32_e32 v0, 0x71c8, v82
	ds_write2_b32 v0, v2, v3 offset1:1
	v_add_u32_e32 v3, 0x400, v80
	s_waitcnt lgkmcnt(0)
	s_barrier
; DEVI uint32_t pack2(float lo, float hi) { f32x2_t v = {lo, hi}; bf16x2_t b = __builtin_convertvector(v, bf16x2_t); return __builtin_bit_cast(uint32_t, b); }
; DEVI void expert_tt_pair(const int TIDX, KAP KA, unsigned char* WSB, int l, int p, unsigned char* smem) {
;     ...
; #pragma unroll
;   for (int u = 0; u < 2; ++u)
; #pragma unroll
;     for (int q = 0; q < 2; ++q) {
;       const int n = nr + 32 * q;
;       const float* sp = tile + u * 4160 + kc * 65 + n;
;       const uint4 o = make_uint4(pack2(sp[0], sp[65]), pack2(sp[130], sp[195]), pack2(sp[260], sp[325]), pack2(sp[390], sp[455]));
;       *(uint4*)(dst + (size_t)(n0[u] + n) * K + k0[u] + kc) = o;
;     }
;   __syncthreads();
	ds_read2_b32 v[8:9], v80 offset1:32
	ds_read2_b32 v[10:11], v80 offset0:65 offset1:97
	ds_read2_b32 v[12:13], v80 offset0:130 offset1:162
	ds_read2_b32 v[14:15], v80 offset0:195 offset1:227
	ds_read2_b32 v[16:17], v3 offset0:4 offset1:36
	ds_read2_b32 v[18:19], v3 offset0:69 offset1:101
	ds_read2_b32 v[20:21], v3 offset0:134 offset1:166
	ds_read2_b32 v[22:23], v3 offset0:199 offset1:231
	v_lshl_add_u64 v[4:5], s[30:31], 0, v[64:65]
	v_lshl_add_u64 v[6:7], v[4:5], 0, s[54:55]
	s_waitcnt lgkmcnt(6)
	v_cvt_pk_bf16_f32 v0, v8, v10
	s_waitcnt lgkmcnt(4)
	v_cvt_pk_bf16_f32 v1, v12, v14
	s_waitcnt lgkmcnt(2)
	v_cvt_pk_bf16_f32 v2, v16, v18
	s_waitcnt lgkmcnt(0)
	v_cvt_pk_bf16_f32 v3, v20, v22
	v_lshl_add_u64 v[24:25], v[24:25], 1, v[6:7]
	v_add_u32_e32 v8, s27, v81
	global_store_dwordx4 v[24:25], v[0:3], off
	s_lshl_b32 s54, s26, 7
	v_add_u32_e32 v22, s25, v79
	v_cvt_pk_bf16_f32 v0, v9, v11
	v_ashrrev_i32_e32 v9, 31, v8
	v_lshlrev_b64 v[8:9], s7, v[8:9]
	v_cvt_pk_bf16_f32 v1, v13, v15
	v_cvt_pk_bf16_f32 v2, v17, v19
	v_cvt_pk_bf16_f32 v3, v21, v23
	v_lshl_add_u64 v[6:7], v[8:9], 1, v[6:7]
	global_store_dwordx4 v[6:7], v[0:3], off
	v_ashrrev_i32_e32 v23, 31, v22
	v_lshlrev_b64 v[22:23], s7, v[22:23]
	v_lshl_add_u64 v[0:1], v[4:5], 0, s[54:55]
	v_add_u32_e32 v3, 0x4000, v80
	v_add_u32_e32 v5, 0x4400, v80
	ds_read2_b32 v[6:7], v3 offset0:64 offset1:96
	ds_read2_b32 v[8:9], v3 offset0:129 offset1:161
	ds_read2_b32 v[10:11], v3 offset0:194 offset1:226
	ds_read2_b32 v[12:13], v5 offset0:3 offset1:35
	ds_read2_b32 v[14:15], v5 offset0:68 offset1:100
	ds_read2_b32 v[16:17], v5 offset0:133 offset1:165
	ds_read2_b32 v[18:19], v5 offset0:198 offset1:230
	v_add_u32_e32 v5, 0x4800, v80
	ds_read2_b32 v[20:21], v5 offset0:7 offset1:39
	s_waitcnt lgkmcnt(6)
	v_cvt_pk_bf16_f32 v2, v6, v8
	s_waitcnt lgkmcnt(4)
	v_cvt_pk_bf16_f32 v3, v10, v12
	s_waitcnt lgkmcnt(2)
	v_cvt_pk_bf16_f32 v4, v14, v16
	v_lshl_add_u64 v[22:23], v[22:23], 1, v[0:1]
	s_waitcnt lgkmcnt(0)
	v_cvt_pk_bf16_f32 v5, v18, v20
	v_add_u32_e32 v6, s25, v81
	s_cmpk_lt_i32 s8, 0x1800
	global_store_dwordx4 v[22:23], v[2:5], off
	s_cselect_b64 s[26:27], -1, 0
	s_and_b64 s[26:27], s[4:5], s[26:27]
	v_cvt_pk_bf16_f32 v2, v7, v9
	v_ashrrev_i32_e32 v7, 31, v6
	v_lshlrev_b64 v[6:7], s7, v[6:7]
	v_cvt_pk_bf16_f32 v3, v11, v13
	v_cvt_pk_bf16_f32 v4, v15, v17
	v_cvt_pk_bf16_f32 v5, v19, v21
	v_lshl_add_u64 v[0:1], v[6:7], 1, v[0:1]
	s_add_i32 s6, s6, s24
	s_mov_b64 s[4:5], 0
	s_andn2_b64 vcc, exec, s[26:27]
	global_store_dwordx4 v[0:1], v[2:5], off
	s_barrier
	s_cbranch_vccz .LBB0_108
	s_branch .LBB0_103

; #define PIN(i) (*(const float* const __attribute__((address_space(4)))*)(KA + 8 * (i)))
; DEVI void expert_tt_pair(const int TIDX, KAP KA, unsigned char* WSB, int l, int p, unsigned char* smem) {
;   float* tile = (float*)smem;
;   bf16_t* WE = (bf16_t*)(WSB + O_WE);
;   const int t = TIDX, n4 = (t & 15) * 4, kr = t >> 4, kc = (t & 7) * 8, nr = t >> 3;
;   const int mat = p >> 6, tp = (p & 63) * 2, kind = mat >> 5, e = mat & 31;
;   const float* src = PIN(kind == 0 ? I_WE1 : (kind == 1 ? I_WE3 : I_WE2)) + ((size_t)l * 32 + e) * 524288;
;   bf16_t* dst = WE + ((size_t)kind * 32 + e) * 524288;
;   const int ld = kind < 2 ? 512 : 1024, K = kind < 2 ? 1024 : 512, nkt = K >> 6;
;   int k0[2], n0[2];
; #pragma unroll
;   for (int u = 0; u < 2; ++u) { const int tt = tp + u; k0[u] = (tt % nkt) * 64; n0[u] = (tt / nkt) * 64; }
;   float4 v[2][4];
; #pragma unroll
;   for (int u = 0; u < 2; ++u)
; #pragma unroll
;     for (int q = 0; q < 4; ++q) v[u][q] = *(const float4*)(src + (size_t)(k0[u] + kr + 16 * q) * ld + n0[u] + n4);
; #pragma unroll
;   for (int u = 0; u < 2; ++u)
; #pragma unroll
;     for (int q = 0; q < 4; ++q) {
;       float* d = tile + u * 4160 + (kr + 16 * q) * 65 + n4;
;       d[0] = v[u][q].x; d[1] = v[u][q].y; d[2] = v[u][q].z; d[3] = v[u][q].w;
;     }
;   __syncthreads();
.LBB0_111:
	s_and_b32 s9, s4, 0x7e
	s_ashr_i32 s6, s8, 11
	s_bfe_u32 s12, s8, 0x50006
	s_cmp_eq_u32 s6, 1
	s_cselect_b32 s7, s22, 0xd0
	s_cmpk_gt_u32 s8, 0x7ff
	s_cselect_b32 s7, s7, 0xc0
	s_add_u32 s10, s88, s7
	s_addc_u32 s11, s89, 0
	s_ashr_i32 s7, s6, 31
	s_load_dwordx2 s[14:15], s[10:11], 0x0
	s_lshl_b32 s13, s12, 21
	s_lshl_b64 s[16:17], s[6:7], 25
	s_lshl_b32 s12, s12, 20
	s_cmp_lt_i32 s6, 2
	s_cselect_b32 s7, 15, 7
	s_cselect_b32 s18, 4, 3
	s_cselect_b32 s19, 9, 10
	s_cselect_b32 s6, 10, 9
	s_or_b32 s21, s9, 1
	s_lshr_b32 s20, s9, s18
	s_lshr_b32 s18, s21, s18
	s_and_b32 s11, s7, s4
	s_lshl_b32 s10, s20, 6
	s_and_b32 s9, s21, s7
	s_lshl_b32 s7, s18, 6
	s_waitcnt lgkmcnt(0)
	s_add_u32 s14, s14, s0
	s_addc_u32 s15, s15, s1
	s_add_u32 s14, s14, s13
	s_addc_u32 s15, s15, 0
	v_lshl_add_u32 v2, s11, 6, v18
	s_add_u32 s13, s2, s16
	v_lshl_add_u64 v[0:1], s[14:15], 0, v[128:129]
	s_addc_u32 s14, s3, s17
	s_lshl_b32 s54, s20, 8
	v_ashrrev_i32_e32 v3, 31, v2
	v_lshl_add_u64 v[6:7], v[0:1], 0, s[54:55]
	v_lshlrev_b64 v[8:9], s19, v[2:3]
	v_lshl_add_u64 v[24:25], v[8:9], 2, v[6:7]
	v_add_u32_e32 v8, 16, v2
	v_ashrrev_i32_e32 v9, 31, v8
	v_lshlrev_b64 v[8:9], s19, v[8:9]
	v_lshl_add_u64 v[26:27], v[8:9], 2, v[6:7]
	v_add_u32_e32 v8, 32, v2
	v_add_u32_e32 v2, 48, v2
	v_ashrrev_i32_e32 v3, 31, v2
	v_lshlrev_b64 v[2:3], s19, v[2:3]
	v_ashrrev_i32_e32 v9, 31, v8
	v_lshl_add_u64 v[14:15], v[2:3], 2, v[6:7]
	v_lshl_add_u32 v2, s9, 6, v18
	v_lshlrev_b64 v[8:9], s19, v[8:9]
	s_lshl_b32 s54, s18, 8
	v_ashrrev_i32_e32 v3, 31, v2
	v_lshl_add_u64 v[16:17], v[8:9], 2, v[6:7]
	v_lshl_add_u64 v[0:1], v[0:1], 0, s[54:55]
	v_lshlrev_b64 v[6:7], s19, v[2:3]
	v_lshl_add_u64 v[12:13], v[6:7], 2, v[0:1]
	v_add_u32_e32 v6, 16, v2
	v_ashrrev_i32_e32 v7, 31, v6
	v_lshlrev_b64 v[6:7], s19, v[6:7]
	v_lshl_add_u64 v[10:11], v[6:7], 2, v[0:1]
	v_add_u32_e32 v6, 32, v2
	v_add_u32_e32 v2, 48, v2
	v_ashrrev_i32_e32 v7, 31, v6
	v_ashrrev_i32_e32 v3, 31, v2
	v_lshlrev_b64 v[6:7], s19, v[6:7]
	v_lshlrev_b64 v[2:3], s19, v[2:3]
	v_lshl_add_u64 v[8:9], v[6:7], 2, v[0:1]
	v_lshl_add_u64 v[6:7], v[2:3], 2, v[0:1]
	global_load_dwordx4 v[132:135], v[24:25], off
	global_load_dwordx4 v[136:139], v[26:27], off
	global_load_dwordx4 v[140:143], v[16:17], off
	global_load_dwordx4 v[144:147], v[14:15], off
	global_load_dwordx4 v[148:151], v[12:13], off
	global_load_dwordx4 v[152:155], v[10:11], off
	global_load_dwordx4 v[156:159], v[8:9], off
	global_load_dwordx4 v[162:165], v[6:7], off
	v_add_u32_e32 v5, 0x1040, v22
	s_add_u32 s12, s13, s12
	s_addc_u32 s13, s14, 0
	v_add_u32_e32 v32, s10, v19
	s_lshl_b32 s54, s11, 7
	v_ashrrev_i32_e32 v33, 31, v32
	v_lshlrev_b64 v[32:33], s6, v[32:33]
	s_add_i32 s8, s8, s84
	s_add_i32 s4, s4, s5
	s_waitcnt vmcnt(7)
	v_mov_b32_e32 v0, v132
	v_mov_b32_e32 v1, v133
	v_mov_b32_e32 v2, v134
	v_mov_b32_e32 v3, v135
	ds_write2_b32 v22, v0, v1 offset1:1
	ds_write2_b32 v22, v2, v3 offset0:2 offset1:3
	s_nop 0
	s_waitcnt vmcnt(6)
	v_mov_b32_e32 v0, v136
	v_mov_b32_e32 v1, v137
	v_mov_b32_e32 v2, v138
	v_mov_b32_e32 v3, v139
	ds_write2_b32 v5, v0, v1 offset1:1
	v_add_u32_e32 v0, 0x1048, v22
	ds_write2_b32 v0, v2, v3 offset1:1
	s_nop 0
	v_add_u32_e32 v5, 0x2080, v22
	s_waitcnt vmcnt(5)
	v_mov_b32_e32 v0, v140
	v_mov_b32_e32 v1, v141
	v_mov_b32_e32 v2, v142
	v_mov_b32_e32 v3, v143
	ds_write2_b32 v5, v0, v1 offset1:1
	v_add_u32_e32 v0, 0x2088, v22
	ds_write2_b32 v0, v2, v3 offset1:1
	s_nop 0
	v_add_u32_e32 v5, 0x30c0, v22
	s_waitcnt vmcnt(4)
	v_mov_b32_e32 v0, v144
	v_mov_b32_e32 v1, v145
	v_mov_b32_e32 v2, v146
	v_mov_b32_e32 v3, v147
	ds_write2_b32 v5, v0, v1 offset1:1
	v_add_u32_e32 v0, 0x30c8, v22
	ds_write2_b32 v0, v2, v3 offset1:1
	s_nop 0
	v_add_u32_e32 v5, 0x4100, v22
	s_waitcnt vmcnt(3)
	v_mov_b32_e32 v0, v148
	v_mov_b32_e32 v1, v149
	v_mov_b32_e32 v2, v150
	v_mov_b32_e32 v3, v151
	ds_write2_b32 v5, v0, v1 offset1:1
	v_add_u32_e32 v0, 0x4108, v22
	ds_write2_b32 v0, v2, v3 offset1:1
	s_nop 0
	v_add_u32_e32 v5, 0x5140, v22
	s_waitcnt vmcnt(2)
	v_mov_b32_e32 v0, v152
	v_mov_b32_e32 v1, v153
	v_mov_b32_e32 v2, v154
	v_mov_b32_e32 v3, v155
	ds_write2_b32 v5, v0, v1 offset1:1
	v_add_u32_e32 v0, 0x5148, v22
	ds_write2_b32 v0, v2, v3 offset1:1
	s_nop 0
	v_add_u32_e32 v5, 0x6180, v22
	s_waitcnt vmcnt(1)
	v_mov_b32_e32 v0, v156
	v_mov_b32_e32 v1, v157
	v_mov_b32_e32 v2, v158
	v_mov_b32_e32 v3, v159
	ds_write2_b32 v5, v0, v1 offset1:1
	v_add_u32_e32 v0, 0x6188, v22
	ds_write2_b32 v0, v2, v3 offset1:1
	s_nop 0
	v_add_u32_e32 v5, 0x71c0, v22
	s_waitcnt vmcnt(0)
	v_mov_b32_e32 v0, v162
	v_mov_b32_e32 v1, v163
	v_mov_b32_e32 v2, v164
	v_mov_b32_e32 v3, v165
	ds_write2_b32 v5, v0, v1 offset1:1
	v_add_u32_e32 v0, 0x71c8, v22
	ds_write2_b32 v0, v2, v3 offset1:1
	v_add_u32_e32 v3, 0x400, v20
	s_waitcnt lgkmcnt(0)
	s_barrier
; DEVI uint32_t pack2(float lo, float hi) { f32x2_t v = {lo, hi}; bf16x2_t b = __builtin_convertvector(v, bf16x2_t); return __builtin_bit_cast(uint32_t, b); }
; DEVI void expert_tt_pair(const int TIDX, KAP KA, unsigned char* WSB, int l, int p, unsigned char* smem) {
;     ...
; #pragma unroll
;   for (int u = 0; u < 2; ++u)
; #pragma unroll
;     for (int q = 0; q < 2; ++q) {
;       const int n = nr + 32 * q;
;       const float* sp = tile + u * 4160 + kc * 65 + n;
;       const uint4 o = make_uint4(pack2(sp[0], sp[65]), pack2(sp[130], sp[195]), pack2(sp[260], sp[325]), pack2(sp[390], sp[455]));
;       *(uint4*)(dst + (size_t)(n0[u] + n) * K + k0[u] + kc) = o;
;     }
;   __syncthreads();
	ds_read2_b32 v[10:11], v20 offset1:32
	ds_read2_b32 v[12:13], v20 offset0:65 offset1:97
	ds_read2_b32 v[14:15], v20 offset0:130 offset1:162
	ds_read2_b32 v[16:17], v20 offset0:195 offset1:227
	ds_read2_b32 v[24:25], v3 offset0:4 offset1:36
	ds_read2_b32 v[26:27], v3 offset0:69 offset1:101
	ds_read2_b32 v[28:29], v3 offset0:134 offset1:166
	ds_read2_b32 v[30:31], v3 offset0:199 offset1:231
	v_mov_b32_e32 v5, v129
	v_lshl_add_u64 v[6:7], s[12:13], 0, v[4:5]
	v_lshl_add_u64 v[8:9], v[6:7], 0, s[54:55]
	s_waitcnt lgkmcnt(6)
	v_cvt_pk_bf16_f32 v0, v10, v12
	s_waitcnt lgkmcnt(4)
	v_cvt_pk_bf16_f32 v1, v14, v16
	s_waitcnt lgkmcnt(2)
	v_cvt_pk_bf16_f32 v2, v24, v26
	s_waitcnt lgkmcnt(0)
	v_cvt_pk_bf16_f32 v3, v28, v30
	v_lshl_add_u64 v[32:33], v[32:33], 1, v[8:9]
	v_add_u32_e32 v10, s10, v21
	global_store_dwordx4 v[32:33], v[0:3], off
	v_add_u32_e32 v30, s7, v19
	s_lshl_b32 s54, s9, 7
	v_cvt_pk_bf16_f32 v0, v11, v13
	v_ashrrev_i32_e32 v11, 31, v10
	v_lshlrev_b64 v[10:11], s6, v[10:11]
	v_cvt_pk_bf16_f32 v1, v15, v17
	v_cvt_pk_bf16_f32 v2, v25, v27
	v_cvt_pk_bf16_f32 v3, v29, v31
	v_lshl_add_u64 v[8:9], v[10:11], 1, v[8:9]
	global_store_dwordx4 v[8:9], v[0:3], off
	v_ashrrev_i32_e32 v31, 31, v30
	v_lshl_add_u64 v[6:7], v[6:7], 0, s[54:55]
	v_add_u32_e32 v1, 0x4000, v20
	v_add_u32_e32 v3, 0x4400, v20
	ds_read2_b32 v[8:9], v1 offset0:64 offset1:96
	ds_read2_b32 v[10:11], v1 offset0:129 offset1:161
	ds_read2_b32 v[12:13], v1 offset0:194 offset1:226
	ds_read2_b32 v[14:15], v3 offset0:3 offset1:35
	ds_read2_b32 v[16:17], v3 offset0:68 offset1:100
	ds_read2_b32 v[24:25], v3 offset0:133 offset1:165
	ds_read2_b32 v[26:27], v3 offset0:198 offset1:230
	v_add_u32_e32 v3, 0x4800, v20
	ds_read2_b32 v[28:29], v3 offset0:7 offset1:39
	v_lshlrev_b64 v[30:31], s6, v[30:31]
	s_waitcnt lgkmcnt(6)
	v_cvt_pk_bf16_f32 v0, v8, v10
	s_waitcnt lgkmcnt(4)
	v_cvt_pk_bf16_f32 v1, v12, v14
	s_waitcnt lgkmcnt(2)
	v_cvt_pk_bf16_f32 v2, v16, v24
	s_waitcnt lgkmcnt(0)
	v_cvt_pk_bf16_f32 v3, v26, v28
	v_lshl_add_u64 v[30:31], v[30:31], 1, v[6:7]
	v_add_u32_e32 v8, s7, v21
	global_store_dwordx4 v[30:31], v[0:3], off
	s_cmpk_gt_i32 s8, 0x17ff
	s_nop 0
	v_cvt_pk_bf16_f32 v0, v9, v11
	v_ashrrev_i32_e32 v9, 31, v8
	v_lshlrev_b64 v[8:9], s6, v[8:9]
	v_cvt_pk_bf16_f32 v1, v13, v15
	v_cvt_pk_bf16_f32 v2, v17, v25
	v_cvt_pk_bf16_f32 v3, v27, v29
	v_lshl_add_u64 v[6:7], v[8:9], 1, v[6:7]
	global_store_dwordx4 v[6:7], v[0:3], off
	s_barrier
	s_cbranch_scc0 .LBB0_111
